# best + NA/FFT outputs written through and no L2 write-back at the P2->P3 barrier
# baseline (speedup 1.0000x reference)
.LBB0_349:
	s_cmp_gt_i32 s83, 3
	s_cselect_b64 s[0:1], -1, 0
	s_and_b64 s[4:5], s[18:19], s[0:1]
	s_andn2_b64 vcc, exec, s[4:5]
	s_cbranch_vccnz .LBB0_403
	s_waitcnt vmcnt(0)
	s_waitcnt vmcnt(0)
	s_barrier
	s_and_saveexec_b64 s[4:5], s[94:95]
	s_cbranch_execz .LBB0_402
	v_mov_b32_e32 v1, 0x23ff0
	ds_read_b32 v2, v1
	ds_read_b32 v3, v1 offset:4
	s_add_u32 s6, s80, 0x2380000
	s_addc_u32 s7, s81, 0
	s_lshl_b32 s8, s87, 8
	s_add_i32 s9, s8, 0x1400
	s_add_i32 s8, s8, 0x2400
	v_mov_b32_e32 v4, s9
	v_mov_b32_e32 v5, 1
	global_atomic_add v6, v4, v5, s[6:7] sc0
	buffer_inv sc1
	s_waitcnt vmcnt(0) lgkmcnt(0)
	v_readfirstlane_b32 s10, v6
	v_readfirstlane_b32 s11, v2
	v_readfirstlane_b32 s16, v3
	s_add_i32 s10, s10, 1
	s_mul_i32 s11, s11, 3
	s_cmp_lg_u32 s10, s11
	s_cbranch_scc1 .Lxb_nl_2
	v_mov_b32_e32 v4, 0x3400
	global_atomic_add v6, v4, v5, s[6:7] sc0
	s_waitcnt vmcnt(0)
	v_readfirstlane_b32 s10, v6
	s_add_i32 s10, s10, 1
	s_mul_i32 s16, s16, 3
	s_cmp_lg_u32 s10, s16
	s_cbranch_scc1 .Lxb_nl_2
	v_mov_b32_e32 v4, 0x2400
	global_atomic_add v4, v5, s[6:7]
	global_atomic_add v4, v5, s[6:7] offset:256
	global_atomic_add v4, v5, s[6:7] offset:512
	global_atomic_add v4, v5, s[6:7] offset:768
	global_atomic_add v4, v5, s[6:7] offset:1024
	global_atomic_add v4, v5, s[6:7] offset:1280
	global_atomic_add v4, v5, s[6:7] offset:1536
	global_atomic_add v4, v5, s[6:7] offset:1792
	global_atomic_add v4, v5, s[6:7] offset:2048
	global_atomic_add v4, v5, s[6:7] offset:2304
	global_atomic_add v4, v5, s[6:7] offset:2560
	global_atomic_add v4, v5, s[6:7] offset:2816
	global_atomic_add v4, v5, s[6:7] offset:3072
	global_atomic_add v4, v5, s[6:7] offset:3328
	global_atomic_add v4, v5, s[6:7] offset:3584
	global_atomic_add v4, v5, s[6:7] offset:3840
	s_branch .Lxb_done_2
